# parameter loads hoisted to top of row loops in P1, P4 and final residual phase (no mid-loop vmcnt waits), on pairk2_prio
# baseline (speedup 1.0000x reference)
.LBB0_113:
	s_ashr_i32 s15, s14, 31
	s_add_i32 s0, s14, 1
	s_ashr_i32 s20, s17, 11
	s_add_i32 s4, s14, 2
	s_add_i32 s8, s14, 3
	s_lshl_b64 s[18:19], s[14:15], 12
	s_ashr_i32 s1, s0, 31
	s_mul_i32 s20, s20, 9
	s_ashr_i32 s5, s4, 31
	s_ashr_i32 s9, s8, 31
	v_lshl_add_u64 v[0:1], v[68:69], 0, s[18:19]
	s_lshl_b64 s[18:19], s[0:1], 12
	s_ashr_i32 s21, s20, 31
	s_lshl_b64 s[26:27], s[4:5], 12
	s_lshl_b64 s[28:29], s[8:9], 12
	v_lshl_add_u64 v[76:77], v[68:69], 0, s[18:19]
	s_lshl_b64 s[18:19], s[20:21], 12
	global_load_dwordx4 v[64:67], v[72:73], off
	global_load_dwordx4 v[36:39], v[0:1], off
	global_load_dwordx4 v[20:23], v[0:1], off offset:1024
	global_load_dwordx4 v[16:19], v[0:1], off offset:2048
	s_nop 0
	global_load_dwordx4 v[0:3], v[0:1], off offset:3072
	s_add_u32 s18, s2, s18
	s_addc_u32 s19, s3, s19
	s_add_u32 s20, s18, 0x1000
	v_lshl_add_u64 v[78:79], v[68:69], 0, s[26:27]
	v_lshl_add_u64 v[80:81], v[68:69], 0, s[28:29]
	global_load_dwordx4 v[52:55], v[76:77], off
	global_load_dwordx4 v[48:51], v[76:77], off offset:1024
	global_load_dwordx4 v[56:59], v[78:79], off
	global_load_dwordx4 v[44:47], v[78:79], off offset:1024
	global_load_dwordx4 v[60:63], v[80:81], off
	global_load_dwordx4 v[40:43], v[80:81], off offset:1024
	global_load_dwordx4 v[24:27], v[76:77], off offset:2048
	global_load_dwordx4 v[4:7], v[76:77], off offset:3072
	global_load_dwordx4 v[28:31], v[78:79], off offset:2048
	global_load_dwordx4 v[8:11], v[78:79], off offset:3072
	global_load_dwordx4 v[32:35], v[80:81], off offset:2048
	global_load_dwordx4 v[12:15], v[80:81], off offset:3072
	s_addc_u32 s21, s19, 0
	global_load_dwordx4 v[94:97], v90, s[20:21]
	global_load_dwordx4 v[98:101], v90, s[18:19]
	s_lshl_b64 s[8:9], s[8:9], 11
	s_lshl_b64 s[0:1], s[0:1], 11
	s_lshl_b64 s[4:5], s[4:5], 11
	v_lshl_add_u64 v[82:83], v[70:71], 0, s[8:9]
	v_lshl_add_u64 v[78:79], v[70:71], 0, s[0:1]
	v_lshl_add_u64 v[80:81], v[70:71], 0, s[4:5]
	s_lshl_b64 s[26:27], s[14:15], 11
	v_lshl_add_u64 v[76:77], v[70:71], 0, s[26:27]
	s_add_i32 s14, s14, s23
	global_load_dwordx4 v[164:167], v91, s[20:21]
	global_load_dwordx4 v[168:171], v[72:73], off offset:1024
	global_load_dwordx4 v[172:175], v90, s[18:19] offset:1024
	global_load_dwordx4 v[176:179], v92, s[20:21]
	global_load_dwordx4 v[180:183], v[72:73], off offset:2048
	global_load_dwordx4 v[184:187], v90, s[18:19] offset:2048
	global_load_dwordx4 v[188:191], v93, s[20:21]
	global_load_dwordx4 v[192:195], v[72:73], off offset:3072
	global_load_dwordx4 v[196:199], v90, s[18:19] offset:3072
	s_waitcnt vmcnt(22)
	v_pk_mul_f32 v[116:117], v[52:53], v[52:53]
	s_waitcnt vmcnt(21)
	v_pk_mul_f32 v[118:119], v[50:51], v[50:51]
	v_pk_mul_f32 v[102:103], v[38:39], v[38:39]
	v_pk_mul_f32 v[104:105], v[36:37], v[36:37]
	v_pk_mul_f32 v[106:107], v[22:23], v[22:23]
	v_pk_mul_f32 v[108:109], v[20:21], v[20:21]
	v_mul_f32_e32 v110, v17, v17
	v_mul_f32_e32 v112, v19, v19
	v_pk_mov_b32 v[114:115], v[104:105], v[102:103] op_sel:[1,0]
	v_mov_b32_e32 v105, v103
	v_pk_mov_b32 v[102:103], v[108:109], v[106:107] op_sel:[1,0]
	v_mov_b32_e32 v109, v107
	v_pk_mul_f32 v[106:107], v[54:55], v[54:55]
	v_pk_mul_f32 v[120:121], v[48:49], v[48:49]
	v_mul_f32_e32 v139, v2, v2
	v_mul_f32_e32 v141, v3, v3
	s_waitcnt vmcnt(20)
	v_pk_mul_f32 v[122:123], v[58:59], v[58:59]
	v_pk_mul_f32 v[124:125], v[56:57], v[56:57]
	s_waitcnt vmcnt(19)
	v_pk_mul_f32 v[126:127], v[46:47], v[46:47]
	v_pk_mul_f32 v[128:129], v[44:45], v[44:45]
	s_waitcnt vmcnt(18)
	v_pk_mul_f32 v[130:131], v[62:63], v[62:63]
	v_pk_mul_f32 v[132:133], v[60:61], v[60:61]
	s_waitcnt vmcnt(17)
	v_pk_mul_f32 v[134:135], v[42:43], v[42:43]
	v_pk_mul_f32 v[136:137], v[40:41], v[40:41]
	v_pk_fma_f32 v[110:111], v[16:17], v[16:17], v[110:111] op_sel_hi:[1,1,0]
	v_pk_fma_f32 v[112:113], v[18:19], v[18:19], v[112:113] op_sel_hi:[1,1,0]
	v_pk_add_f32 v[102:103], v[102:103], v[108:109]
	v_pk_mov_b32 v[108:109], v[116:117], v[106:107] op_sel:[1,0]
	v_mov_b32_e32 v117, v107
	v_pk_mov_b32 v[106:107], v[120:121], v[118:119] op_sel:[1,0]
	v_mov_b32_e32 v121, v119
	s_waitcnt vmcnt(16)
	v_mul_f32_e32 v140, v25, v25
	v_mul_f32_e32 v142, v27, v27
	v_pk_add_f32 v[104:105], v[114:115], v[104:105]
	v_pk_mov_b32 v[114:115], v[124:125], v[122:123] op_sel:[1,0]
	v_mov_b32_e32 v125, v123
	v_pk_mov_b32 v[118:119], v[128:129], v[126:127] op_sel:[1,0]
	v_mov_b32_e32 v129, v127
	v_pk_mov_b32 v[122:123], v[132:133], v[130:131] op_sel:[1,0]
	v_mov_b32_e32 v133, v131
	v_pk_mov_b32 v[126:127], v[136:137], v[134:135] op_sel:[1,0]
	v_mov_b32_e32 v137, v135
	v_mov_b32_e32 v111, v139
	v_mov_b32_e32 v113, v141
	v_pk_add_f32 v[108:109], v[108:109], v[116:117]
	v_pk_add_f32 v[106:107], v[106:107], v[120:121]
	v_mul_f32_e32 v149, v0, v0
	v_mul_f32_e32 v151, v1, v1
	s_waitcnt vmcnt(15)
	v_mul_f32_e32 v152, v6, v6
	v_mul_f32_e32 v153, v7, v7
	s_waitcnt vmcnt(14)
	v_mul_f32_e32 v144, v29, v29
	v_mul_f32_e32 v146, v31, v31
	s_waitcnt vmcnt(12)
	v_mul_f32_e32 v148, v33, v33
	v_mul_f32_e32 v150, v35, v35
	v_mul_f32_e32 v158, v4, v4
	v_mul_f32_e32 v159, v5, v5
	v_pk_fma_f32 v[130:131], v[24:25], v[24:25], v[140:141] op_sel_hi:[1,1,0]
	v_pk_fma_f32 v[134:135], v[26:27], v[26:27], v[142:143] op_sel_hi:[1,1,0]
	v_pk_add_f32 v[110:111], v[110:111], v[112:113]
	v_pk_add_f32 v[112:113], v[114:115], v[124:125]
	v_pk_add_f32 v[114:115], v[118:119], v[128:129]
	v_pk_add_f32 v[116:117], v[122:123], v[132:133]
	v_pk_add_f32 v[118:119], v[126:127], v[136:137]
	v_pk_add_f32 v[104:105], v[104:105], v[104:105] op_sel:[0,1] op_sel_hi:[1,0]
	v_pk_add_f32 v[102:103], v[102:103], v[102:103] op_sel:[0,1] op_sel_hi:[1,0]
	v_pk_add_f32 v[108:109], v[108:109], v[108:109] op_sel:[0,1] op_sel_hi:[1,0]
	v_pk_add_f32 v[106:107], v[106:107], v[106:107] op_sel:[0,1] op_sel_hi:[1,0]
	v_mul_f32_e32 v154, v10, v10
	v_mul_f32_e32 v155, v11, v11
	s_waitcnt vmcnt(11)
	v_mul_f32_e32 v156, v14, v14
	v_mul_f32_e32 v157, v15, v15
	v_mul_f32_e32 v160, v8, v8
	v_mul_f32_e32 v161, v9, v9
	v_mul_f32_e32 v162, v12, v12
	v_mul_f32_e32 v163, v13, v13
	v_pk_fma_f32 v[140:141], v[28:29], v[28:29], v[144:145] op_sel_hi:[1,1,0]
	v_pk_fma_f32 v[142:143], v[30:31], v[30:31], v[146:147] op_sel_hi:[1,1,0]
	v_pk_fma_f32 v[144:145], v[32:33], v[32:33], v[148:149] op_sel_hi:[1,1,0]
	v_pk_fma_f32 v[146:147], v[34:35], v[34:35], v[150:151] op_sel_hi:[1,1,0]
	v_mov_b32_e32 v131, v152
	v_mov_b32_e32 v135, v153
	v_mov_b32_e32 v105, v149
	v_mov_b32_e32 v103, v151
	v_pk_add_f32 v[112:113], v[112:113], v[112:113] op_sel:[0,1] op_sel_hi:[1,0]
	v_pk_add_f32 v[114:115], v[114:115], v[114:115] op_sel:[0,1] op_sel_hi:[1,0]
	v_pk_add_f32 v[116:117], v[116:117], v[116:117] op_sel:[0,1] op_sel_hi:[1,0]
	v_pk_add_f32 v[118:119], v[118:119], v[118:119] op_sel:[0,1] op_sel_hi:[1,0]
	s_waitcnt vmcnt(10)
	v_pk_add_f32 v[96:97], v[96:97], 1.0 op_sel_hi:[1,0]
	v_mov_b32_e32 v109, v158
	v_mov_b32_e32 v107, v159
	v_mov_b32_e32 v141, v154
	v_mov_b32_e32 v143, v155
	v_mov_b32_e32 v145, v156
	v_mov_b32_e32 v147, v157
	v_pk_add_f32 v[120:121], v[130:131], v[134:135]
	v_pk_add_f32 v[94:95], v[94:95], 1.0 op_sel_hi:[1,0]
	v_pk_add_f32 v[102:103], v[104:105], v[102:103]
	v_mov_b32_e32 v113, v160
	v_mov_b32_e32 v115, v161
	v_mov_b32_e32 v117, v162
	v_mov_b32_e32 v119, v163
	v_pk_mul_f32 v[66:67], v[66:67], v[96:97]
	v_pk_add_f32 v[96:97], v[108:109], v[106:107]
	v_pk_add_f32 v[122:123], v[140:141], v[142:143]
	v_pk_add_f32 v[124:125], v[144:145], v[146:147]
	v_pk_mul_f32 v[64:65], v[64:65], v[94:95]
	v_pk_add_f32 v[94:95], v[102:103], v[110:111]
	v_pk_add_f32 v[102:103], v[112:113], v[114:115]
	v_pk_add_f32 v[104:105], v[116:117], v[118:119]
	v_pk_add_f32 v[96:97], v[96:97], v[120:121]
	v_pk_add_f32 v[102:103], v[102:103], v[122:123]
	v_pk_add_f32 v[104:105], v[104:105], v[124:125]
	v_mov_b32_e32 v107, v94
	v_mov_b32_e32 v106, v96
	v_mov_b32_e32 v94, v97
	v_mov_b32_e32 v96, v104
	v_mov_b32_e32 v97, v102
	v_mov_b32_e32 v102, v105
	v_pk_add_f32 v[94:95], v[106:107], v[94:95]
	v_pk_add_f32 v[96:97], v[96:97], v[102:103]
	ds_bpermute_b32 v103, v84, v95
	ds_bpermute_b32 v102, v84, v94
	ds_bpermute_b32 v105, v84, v97
	ds_bpermute_b32 v104, v84, v96
	s_waitcnt lgkmcnt(2)
	v_pk_add_f32 v[94:95], v[94:95], v[102:103]
	ds_bpermute_b32 v103, v85, v95
	s_waitcnt lgkmcnt(1)
	v_pk_add_f32 v[96:97], v[96:97], v[104:105]
	ds_bpermute_b32 v102, v85, v94
	ds_bpermute_b32 v105, v85, v97
	ds_bpermute_b32 v104, v85, v96
	s_waitcnt lgkmcnt(2)
	v_pk_add_f32 v[94:95], v[94:95], v[102:103]
	ds_bpermute_b32 v103, v86, v95
	s_waitcnt lgkmcnt(1)
	v_pk_add_f32 v[96:97], v[96:97], v[104:105]
	ds_bpermute_b32 v102, v86, v94
	ds_bpermute_b32 v105, v86, v97
	ds_bpermute_b32 v104, v86, v96
	s_waitcnt lgkmcnt(2)
	v_pk_add_f32 v[94:95], v[94:95], v[102:103]
	ds_bpermute_b32 v103, v87, v95
	s_waitcnt lgkmcnt(1)
	v_pk_add_f32 v[96:97], v[96:97], v[104:105]
	ds_bpermute_b32 v102, v87, v94
	ds_bpermute_b32 v105, v87, v97
	ds_bpermute_b32 v104, v87, v96
	s_waitcnt lgkmcnt(2)
	v_pk_add_f32 v[94:95], v[94:95], v[102:103]
	ds_bpermute_b32 v103, v88, v95
	s_waitcnt lgkmcnt(1)
	v_pk_add_f32 v[96:97], v[96:97], v[104:105]
	ds_bpermute_b32 v102, v88, v94
	ds_bpermute_b32 v105, v88, v97
	ds_bpermute_b32 v104, v88, v96
	s_waitcnt lgkmcnt(2)
	v_pk_add_f32 v[94:95], v[94:95], v[102:103]
	ds_bpermute_b32 v103, v89, v95
	s_waitcnt lgkmcnt(1)
	v_pk_add_f32 v[96:97], v[96:97], v[104:105]
	ds_bpermute_b32 v102, v89, v94
	ds_bpermute_b32 v105, v89, v97
	ds_bpermute_b32 v104, v89, v96
	s_waitcnt lgkmcnt(2)
	v_pk_add_f32 v[94:95], v[94:95], v[102:103]
	s_nop 0
	v_pk_fma_f32 v[94:95], v[94:95], s[16:17], v[74:75] op_sel_hi:[1,0,0]
	s_waitcnt lgkmcnt(0)
	v_pk_add_f32 v[96:97], v[96:97], v[104:105]
	v_mul_f32_e32 v103, 0x4b800000, v95
	v_pk_fma_f32 v[96:97], v[96:97], s[16:17], v[74:75] op_sel_hi:[1,0,0]
	v_cmp_gt_f32_e64 s[8:9], s24, v95
	v_mul_f32_e32 v102, 0x4b800000, v94
	v_cmp_gt_f32_e32 vcc, s24, v94
	v_mul_f32_e32 v104, 0x4b800000, v96
	v_cmp_gt_f32_e64 s[0:1], s24, v96
	v_mul_f32_e32 v105, 0x4b800000, v97
	v_cmp_gt_f32_e64 s[4:5], s24, v97
	v_cndmask_b32_e64 v95, v95, v103, s[8:9]
	v_cndmask_b32_e32 v94, v94, v102, vcc
	v_cndmask_b32_e64 v97, v97, v105, s[4:5]
	v_cndmask_b32_e64 v96, v96, v104, s[0:1]
	v_rsq_f32_e32 v95, v95
	v_rsq_f32_e32 v102, v94
	v_rsq_f32_e32 v97, v97
	v_rsq_f32_e32 v103, v96
	v_mul_f32_e32 v94, 0x45800000, v95
	v_mul_f32_e32 v96, 0x45800000, v102
	v_mul_f32_e32 v104, 0x45800000, v97
	v_mul_f32_e32 v105, 0x45800000, v103
	v_cndmask_b32_e64 v94, v95, v94, s[8:9]
	v_cndmask_b32_e32 v96, v102, v96, vcc
	v_cndmask_b32_e64 v102, v97, v104, s[4:5]
	v_cndmask_b32_e64 v104, v103, v105, s[0:1]
	v_pk_mul_f32 v[36:37], v[36:37], v[94:95] op_sel_hi:[1,0]
	v_pk_mul_f32 v[38:39], v[38:39], v[94:95] op_sel_hi:[1,0]
	v_pk_mul_f32 v[52:53], v[52:53], v[96:97] op_sel_hi:[1,0]
	v_pk_mul_f32 v[54:55], v[54:55], v[96:97] op_sel_hi:[1,0]
	v_pk_mul_f32 v[56:57], v[56:57], v[102:103] op_sel_hi:[1,0]
	v_pk_mul_f32 v[58:59], v[58:59], v[102:103] op_sel_hi:[1,0]
	v_pk_mul_f32 v[60:61], v[60:61], v[104:105] op_sel_hi:[1,0]
	v_pk_mul_f32 v[62:63], v[62:63], v[104:105] op_sel_hi:[1,0]
	s_waitcnt vmcnt(0)
	v_pk_fma_f32 v[38:39], v[38:39], v[66:67], v[100:101]
	v_pk_fma_f32 v[36:37], v[36:37], v[64:65], v[98:99]
	v_pk_fma_f32 v[54:55], v[54:55], v[66:67], v[100:101]
	v_pk_fma_f32 v[58:59], v[66:67], v[58:59], v[100:101]
	v_pk_fma_f32 v[62:63], v[66:67], v[62:63], v[100:101]
	v_pk_fma_f32 v[52:53], v[52:53], v[64:65], v[98:99]
	v_pk_fma_f32 v[56:57], v[64:65], v[56:57], v[98:99]
	v_pk_fma_f32 v[60:61], v[64:65], v[60:61], v[98:99]
	v_cvt_pk_bf16_f32 v36, v36, v37
	v_cvt_pk_bf16_f32 v37, v38, v39
	v_cvt_pk_bf16_f32 v38, v52, v53
	v_cvt_pk_bf16_f32 v39, v54, v55
	v_cvt_pk_bf16_f32 v52, v56, v57
	v_cvt_pk_bf16_f32 v53, v58, v59
	v_cvt_pk_bf16_f32 v54, v60, v61
	v_cvt_pk_bf16_f32 v55, v62, v63
	global_store_dwordx2 v[76:77], v[36:37], off
	global_store_dwordx2 v[78:79], v[38:39], off
	global_store_dwordx2 v[80:81], v[52:53], off
	global_store_dwordx2 v[82:83], v[54:55], off
	s_nop 0
	v_pk_mul_f32 v[20:21], v[20:21], v[94:95] op_sel_hi:[1,0]
	v_pk_mul_f32 v[22:23], v[22:23], v[94:95] op_sel_hi:[1,0]
	v_pk_mul_f32 v[48:49], v[48:49], v[96:97] op_sel_hi:[1,0]
	v_pk_mul_f32 v[50:51], v[50:51], v[96:97] op_sel_hi:[1,0]
	v_pk_mul_f32 v[44:45], v[44:45], v[102:103] op_sel_hi:[1,0]
	v_pk_mul_f32 v[46:47], v[46:47], v[102:103] op_sel_hi:[1,0]
	v_pk_mul_f32 v[40:41], v[40:41], v[104:105] op_sel_hi:[1,0]
	v_pk_mul_f32 v[42:43], v[42:43], v[104:105] op_sel_hi:[1,0]
	v_pk_mul_f32 v[16:17], v[16:17], v[94:95] op_sel_hi:[1,0]
	v_pk_mul_f32 v[18:19], v[18:19], v[94:95] op_sel_hi:[1,0]
	v_pk_mul_f32 v[24:25], v[24:25], v[96:97] op_sel_hi:[1,0]
	v_pk_mul_f32 v[26:27], v[26:27], v[96:97] op_sel_hi:[1,0]
	v_pk_mul_f32 v[28:29], v[28:29], v[102:103] op_sel_hi:[1,0]
	v_pk_mul_f32 v[30:31], v[30:31], v[102:103] op_sel_hi:[1,0]
	v_pk_mul_f32 v[32:33], v[32:33], v[104:105] op_sel_hi:[1,0]
	v_pk_mul_f32 v[34:35], v[34:35], v[104:105] op_sel_hi:[1,0]
	v_pk_mul_f32 v[0:1], v[0:1], v[94:95] op_sel_hi:[1,0]
	v_pk_mul_f32 v[2:3], v[2:3], v[94:95] op_sel_hi:[1,0]
	s_add_i32 s17, s17, s22
	v_pk_mul_f32 v[4:5], v[4:5], v[96:97] op_sel_hi:[1,0]
	v_pk_mul_f32 v[6:7], v[6:7], v[96:97] op_sel_hi:[1,0]
	v_pk_mul_f32 v[8:9], v[8:9], v[102:103] op_sel_hi:[1,0]
	v_pk_mul_f32 v[10:11], v[10:11], v[102:103] op_sel_hi:[1,0]
	v_pk_mul_f32 v[12:13], v[12:13], v[104:105] op_sel_hi:[1,0]
	v_pk_mul_f32 v[14:15], v[14:15], v[104:105] op_sel_hi:[1,0]
	s_cmpk_lt_i32 s17, 0x4000
	v_pk_add_f32 v[38:39], v[166:167], 1.0 op_sel_hi:[1,0]
	v_pk_add_f32 v[36:37], v[164:165], 1.0 op_sel_hi:[1,0]
	v_pk_mul_f32 v[38:39], v[170:171], v[38:39]
	v_pk_mul_f32 v[36:37], v[168:169], v[36:37]
	v_pk_fma_f32 v[22:23], v[22:23], v[38:39], v[174:175]
	v_pk_fma_f32 v[20:21], v[20:21], v[36:37], v[172:173]
	v_pk_fma_f32 v[50:51], v[50:51], v[38:39], v[174:175]
	v_pk_fma_f32 v[48:49], v[48:49], v[36:37], v[172:173]
	v_pk_fma_f32 v[46:47], v[46:47], v[38:39], v[174:175]
	v_pk_fma_f32 v[44:45], v[44:45], v[36:37], v[172:173]
	v_pk_fma_f32 v[38:39], v[38:39], v[42:43], v[174:175]
	v_pk_fma_f32 v[36:37], v[36:37], v[40:41], v[172:173]
	v_cvt_pk_bf16_f32 v20, v20, v21
	v_cvt_pk_bf16_f32 v21, v22, v23
	v_cvt_pk_bf16_f32 v22, v48, v49
	v_cvt_pk_bf16_f32 v23, v50, v51
	v_cvt_pk_bf16_f32 v40, v44, v45
	v_cvt_pk_bf16_f32 v41, v46, v47
	v_cvt_pk_bf16_f32 v36, v36, v37
	v_cvt_pk_bf16_f32 v37, v38, v39
	global_store_dwordx2 v[76:77], v[20:21], off offset:512
	global_store_dwordx2 v[78:79], v[22:23], off offset:512
	global_store_dwordx2 v[80:81], v[40:41], off offset:512
	global_store_dwordx2 v[82:83], v[36:37], off offset:512
	s_nop 0
	v_pk_add_f32 v[22:23], v[178:179], 1.0 op_sel_hi:[1,0]
	v_pk_add_f32 v[20:21], v[176:177], 1.0 op_sel_hi:[1,0]
	v_pk_mul_f32 v[22:23], v[182:183], v[22:23]
	v_pk_mul_f32 v[20:21], v[180:181], v[20:21]
	v_pk_fma_f32 v[18:19], v[18:19], v[22:23], v[186:187]
	v_pk_fma_f32 v[16:17], v[16:17], v[20:21], v[184:185]
	v_pk_fma_f32 v[26:27], v[26:27], v[22:23], v[186:187]
	v_pk_fma_f32 v[24:25], v[24:25], v[20:21], v[184:185]
	v_pk_fma_f32 v[30:31], v[30:31], v[22:23], v[186:187]
	v_pk_fma_f32 v[28:29], v[28:29], v[20:21], v[184:185]
	v_pk_fma_f32 v[22:23], v[34:35], v[22:23], v[186:187]
	v_pk_fma_f32 v[20:21], v[32:33], v[20:21], v[184:185]
	v_cvt_pk_bf16_f32 v16, v16, v17
	v_cvt_pk_bf16_f32 v17, v18, v19
	v_cvt_pk_bf16_f32 v18, v24, v25
	v_cvt_pk_bf16_f32 v19, v26, v27
	v_cvt_pk_bf16_f32 v24, v28, v29
	v_cvt_pk_bf16_f32 v25, v30, v31
	v_cvt_pk_bf16_f32 v20, v20, v21
	v_cvt_pk_bf16_f32 v21, v22, v23
	global_store_dwordx2 v[76:77], v[16:17], off offset:1024
	global_store_dwordx2 v[78:79], v[18:19], off offset:1024
	global_store_dwordx2 v[80:81], v[24:25], off offset:1024
	global_store_dwordx2 v[82:83], v[20:21], off offset:1024
	s_nop 0
	v_pk_add_f32 v[18:19], v[190:191], 1.0 op_sel_hi:[1,0]
	v_pk_add_f32 v[16:17], v[188:189], 1.0 op_sel_hi:[1,0]
	v_pk_mul_f32 v[18:19], v[194:195], v[18:19]
	v_pk_mul_f32 v[16:17], v[192:193], v[16:17]
	v_pk_fma_f32 v[2:3], v[2:3], v[18:19], v[198:199]
	v_pk_fma_f32 v[0:1], v[0:1], v[16:17], v[196:197]
	v_pk_fma_f32 v[6:7], v[6:7], v[18:19], v[198:199]
	v_pk_fma_f32 v[4:5], v[4:5], v[16:17], v[196:197]
	v_pk_fma_f32 v[10:11], v[10:11], v[18:19], v[198:199]
	v_pk_fma_f32 v[8:9], v[8:9], v[16:17], v[196:197]
	v_pk_fma_f32 v[14:15], v[14:15], v[18:19], v[198:199]
	v_pk_fma_f32 v[12:13], v[12:13], v[16:17], v[196:197]
	v_cvt_pk_bf16_f32 v0, v0, v1
	v_cvt_pk_bf16_f32 v1, v2, v3
	v_cvt_pk_bf16_f32 v2, v4, v5
	v_cvt_pk_bf16_f32 v3, v6, v7
	v_cvt_pk_bf16_f32 v4, v8, v9
	v_cvt_pk_bf16_f32 v5, v10, v11
	v_cvt_pk_bf16_f32 v6, v12, v13
	v_cvt_pk_bf16_f32 v7, v14, v15
	global_store_dwordx2 v[76:77], v[0:1], off offset:1536
	global_store_dwordx2 v[78:79], v[2:3], off offset:1536
	global_store_dwordx2 v[80:81], v[4:5], off offset:1536
	global_store_dwordx2 v[82:83], v[6:7], off offset:1536
	s_cbranch_scc1 .LBB0_113

.LBB0_316:
	s_ashr_i32 s18, s9, 12
	s_ashr_i32 s5, s4, 31
	s_add_i32 s0, s4, 1
	s_mul_i32 s18, s18, 9
	s_lshl_b64 s[14:15], s[4:5], 11
	s_lshl_b64 s[16:17], s[4:5], 12
	s_ashr_i32 s1, s0, 31
	s_ashr_i32 s19, s18, 31
	v_lshl_add_u64 v[4:5], v[40:41], 0, s[14:15]
	v_lshl_add_u64 v[6:7], v[42:43], 0, s[16:17]
	s_lshl_b64 s[16:17], s[0:1], 12
	v_lshl_add_u64 v[66:67], v[44:45], 0, s[14:15]
	s_lshl_b64 s[14:15], s[18:19], 12
	s_add_u32 s5, s2, s14
	s_addc_u32 s19, s3, s15
	s_add_u32 s14, s5, 0x2000
	global_load_dwordx4 v[32:35], v[48:49], off
	global_load_dwordx2 v[86:87], v[4:5], off
	global_load_dwordx2 v[84:85], v[4:5], off offset:512
	global_load_dwordx2 v[82:83], v[4:5], off offset:1024
	global_load_dwordx2 v[80:81], v[4:5], off offset:1536
	global_load_dwordx2 v[78:79], v[4:5], off offset:2048
	global_load_dwordx2 v[76:77], v[4:5], off offset:2560
	global_load_dwordx2 v[74:75], v[4:5], off offset:3072
	global_load_dwordx2 v[72:73], v[4:5], off offset:3584
	global_load_dwordx4 v[24:27], v[6:7], off
	global_load_dwordx4 v[16:19], v[6:7], off offset:1024
	global_load_dwordx4 v[8:11], v[6:7], off offset:2048
	global_load_dwordx4 v[0:3], v[6:7], off offset:3072
	v_lshl_add_u64 v[36:37], v[42:43], 0, s[16:17]
	s_addc_u32 s15, s19, 0
	global_load_dwordx4 v[28:31], v[36:37], off
	global_load_dwordx4 v[20:23], v[36:37], off offset:1024
	global_load_dwordx4 v[12:15], v[36:37], off offset:2048
	global_load_dwordx4 v[4:7], v[36:37], off offset:3072
	s_lshl_b64 s[0:1], s[0:1], 11
	global_load_dwordx4 v[36:39], v94, s[14:15]
	s_add_u32 s16, s5, 0x3000
	s_addc_u32 s17, s19, 0
	s_add_u32 s18, s5, 0x4000
	v_lshl_add_u64 v[68:69], v[44:45], 0, s[0:1]
	s_addc_u32 s19, s19, 0
	s_and_b32 s0, s21, 0x8000
	s_and_b32 s1, s9, 0xfffff000
	s_and_b32 s5, s4, 0xffe
	s_add_i32 s0, s0, s1
	s_or_b32 s0, s0, s5
	s_ashr_i32 s1, s0, 31
	s_lshl_b64 s[0:1], s[0:1], 11
	v_lshl_add_u64 v[70:71], v[46:47], 0, s[0:1]
	s_add_i32 s21, s21, s22
	s_add_i32 s4, s4, s23
	global_load_dwordx4 v[152:155], v95, s[14:15]
	global_load_dwordx4 v[156:159], v[50:51], off
	global_load_dwordx4 v[160:163], v96, s[14:15]
	global_load_dwordx4 v[164:167], v[52:53], off
	global_load_dwordx4 v[168:171], v97, s[14:15]
	global_load_dwordx4 v[172:175], v[54:55], off
	global_load_dwordx4 v[176:179], v94, s[18:19]
	global_load_dwordx4 v[180:183], v[56:57], off
	global_load_dwordx4 v[184:187], v94, s[16:17]
	global_load_dwordx4 v[188:191], v95, s[18:19]
	global_load_dwordx4 v[192:195], v[58:59], off
	global_load_dwordx4 v[196:199], v95, s[16:17]
	global_load_dwordx4 v[200:203], v96, s[18:19]
	global_load_dwordx4 v[204:207], v[60:61], off
	global_load_dwordx4 v[220:223], v96, s[16:17]
	global_load_dwordx4 v[224:227], v97, s[18:19]
	global_load_dwordx4 v[228:231], v[62:63], off
	global_load_dwordx4 v[232:235], v97, s[16:17]
	s_waitcnt vmcnt(34)
	v_lshlrev_b32_e32 v98, 16, v86
	v_and_b32_e32 v99, 0xffff0000, v86
	v_lshlrev_b32_e32 v86, 16, v87
	v_and_b32_e32 v87, 0xffff0000, v87
	s_waitcnt vmcnt(33)
	v_lshlrev_b32_e32 v101, 16, v85
	v_lshlrev_b32_e32 v100, 16, v84
	v_and_b32_e32 v85, 0xffff0000, v85
	v_and_b32_e32 v84, 0xffff0000, v84
	s_waitcnt vmcnt(30)
	v_lshlrev_b32_e32 v108, 16, v78
	v_and_b32_e32 v109, 0xffff0000, v78
	v_lshlrev_b32_e32 v78, 16, v79
	v_and_b32_e32 v79, 0xffff0000, v79
	s_waitcnt vmcnt(29)
	v_lshlrev_b32_e32 v111, 16, v77
	v_lshlrev_b32_e32 v110, 16, v76
	v_and_b32_e32 v77, 0xffff0000, v77
	v_and_b32_e32 v76, 0xffff0000, v76
	v_lshlrev_b32_e32 v102, 16, v82
	v_and_b32_e32 v103, 0xffff0000, v82
	v_lshlrev_b32_e32 v82, 16, v83
	v_and_b32_e32 v83, 0xffff0000, v83
	v_lshlrev_b32_e32 v105, 16, v80
	s_waitcnt vmcnt(27)
	v_lshlrev_b32_e32 v115, 16, v72
	v_mul_f32_e32 v104, v87, v87
	v_pk_mul_f32 v[118:119], v[84:85], v[84:85]
	v_mul_f32_e32 v114, v99, v99
	v_mul_f32_e32 v124, v79, v79
	v_pk_mul_f32 v[126:127], v[76:77], v[76:77]
	v_mul_f32_e32 v128, v109, v109
	v_and_b32_e32 v107, 0xffff0000, v80
	v_lshlrev_b32_e32 v112, 16, v74
	v_and_b32_e32 v113, 0xffff0000, v74
	v_lshlrev_b32_e32 v74, 16, v75
	v_and_b32_e32 v75, 0xffff0000, v75
	v_mov_b32_e32 v121, v105
	v_mul_f32_e32 v120, v103, v103
	v_mul_f32_e32 v122, v83, v83
	v_mov_b32_e32 v123, v115
	v_mov_b32_e32 v134, v100
	v_mov_b32_e32 v135, v84
	v_mov_b32_e32 v84, v101
	v_mov_b32_e32 v136, v110
	v_mov_b32_e32 v137, v76
	v_mov_b32_e32 v76, v111
	v_pk_fma_f32 v[140:141], v[86:87], v[86:87], v[104:105] op_sel_hi:[1,1,0]
	v_pk_fma_f32 v[100:101], v[100:101], v[100:101], v[118:119]
	v_pk_fma_f32 v[118:119], v[98:99], v[98:99], v[114:115] op_sel_hi:[1,1,0]
	v_pk_fma_f32 v[124:125], v[78:79], v[78:79], v[124:125] op_sel_hi:[1,1,0]
	v_pk_fma_f32 v[110:111], v[110:111], v[110:111], v[126:127]
	v_pk_fma_f32 v[126:127], v[108:109], v[108:109], v[128:129] op_sel_hi:[1,1,0]
	v_lshlrev_b32_e32 v80, 16, v81
	v_and_b32_e32 v81, 0xffff0000, v81
	v_and_b32_e32 v117, 0xffff0000, v72
	v_lshlrev_b32_e32 v72, 16, v73
	v_and_b32_e32 v73, 0xffff0000, v73
	v_mul_f32_e32 v133, v107, v107
	v_mul_f32_e32 v130, v113, v113
	v_mul_f32_e32 v132, v75, v75
	v_pk_fma_f32 v[142:143], v[102:103], v[102:103], v[120:121] op_sel_hi:[1,1,0]
	v_pk_fma_f32 v[144:145], v[82:83], v[82:83], v[122:123] op_sel_hi:[1,1,0]
	v_mov_b32_e32 v104, v118
	v_mov_b32_e32 v120, v140
	v_mov_b32_e32 v114, v126
	v_mov_b32_e32 v122, v124
	v_mul_f32_e32 v139, v80, v80
	v_mul_f32_e32 v146, v81, v81
	v_mul_f32_e32 v147, v117, v117
	v_mul_f32_e32 v148, v72, v72
	v_mul_f32_e32 v149, v73, v73
	v_mov_b32_e32 v106, v105
	v_mov_b32_e32 v116, v115
	v_pk_fma_f32 v[128:129], v[112:113], v[112:113], v[130:131] op_sel_hi:[1,1,0]
	v_pk_fma_f32 v[130:131], v[74:75], v[74:75], v[132:133] op_sel_hi:[1,1,0]
	v_pk_add_f32 v[118:119], v[118:119], v[140:141]
	v_pk_add_f32 v[100:101], v[100:101], v[100:101] op_sel:[0,1] op_sel_hi:[1,0]
	v_pk_add_f32 v[124:125], v[126:127], v[124:125]
	v_pk_add_f32 v[110:111], v[110:111], v[110:111] op_sel:[0,1] op_sel_hi:[1,0]
	v_pk_mul_f32 v[104:105], v[104:105], v[120:121]
	v_pk_mul_f32 v[114:115], v[114:115], v[122:123]
	v_mov_b32_e32 v143, v139
	v_mov_b32_e32 v145, v146
	v_mov_b32_e32 v129, v148
	v_mov_b32_e32 v131, v149
	v_mov_b32_e32 v101, v133
	v_mov_b32_e32 v111, v147
	v_mov_b32_e32 v119, v105
	v_mov_b32_e32 v125, v115
	v_pk_add_f32 v[120:121], v[142:143], v[144:145]
	v_pk_add_f32 v[122:123], v[128:129], v[130:131]
	s_waitcnt vmcnt(0)
	v_pk_mul_f32 v[34:35], v[38:39], v[34:35]
	v_pk_mul_f32 v[32:33], v[36:37], v[32:33]
	v_pk_add_f32 v[36:37], v[118:119], v[100:101]
	v_pk_add_f32 v[38:39], v[124:125], v[110:111]
	v_pk_add_f32 v[36:37], v[36:37], v[120:121]
	v_pk_add_f32 v[38:39], v[38:39], v[122:123]
	v_mov_b32_e32 v101, v36
	v_mov_b32_e32 v100, v38
	v_mov_b32_e32 v36, v39
	v_pk_add_f32 v[36:37], v[100:101], v[36:37]
	ds_bpermute_b32 v39, v88, v37
	ds_bpermute_b32 v38, v88, v36
	s_waitcnt lgkmcnt(0)
	v_pk_add_f32 v[36:37], v[36:37], v[38:39]
	ds_bpermute_b32 v39, v89, v37
	ds_bpermute_b32 v38, v89, v36
	s_waitcnt lgkmcnt(0)
	v_pk_add_f32 v[36:37], v[36:37], v[38:39]
	ds_bpermute_b32 v39, v90, v37
	ds_bpermute_b32 v38, v90, v36
	s_waitcnt lgkmcnt(0)
	v_pk_add_f32 v[36:37], v[36:37], v[38:39]
	ds_bpermute_b32 v39, v91, v37
	ds_bpermute_b32 v38, v91, v36
	s_waitcnt lgkmcnt(0)
	v_pk_add_f32 v[36:37], v[36:37], v[38:39]
	ds_bpermute_b32 v39, v92, v37
	ds_bpermute_b32 v38, v92, v36
	s_waitcnt lgkmcnt(0)
	v_pk_add_f32 v[36:37], v[36:37], v[38:39]
	ds_bpermute_b32 v39, v93, v37
	ds_bpermute_b32 v38, v93, v36
	s_waitcnt lgkmcnt(0)
	v_pk_add_f32 v[36:37], v[36:37], v[38:39]
	s_nop 0
	v_pk_fma_f32 v[36:37], v[36:37], s[8:9], v[64:65] op_sel_hi:[1,0,0]
	s_nop 0
	v_mul_f32_e32 v38, 0x4b800000, v37
	v_cmp_gt_f32_e64 s[0:1], s24, v37
	v_mul_f32_e32 v39, 0x4b800000, v36
	v_cmp_gt_f32_e32 vcc, s24, v36
	v_cndmask_b32_e64 v37, v37, v38, s[0:1]
	v_rsq_f32_e32 v37, v37
	v_cndmask_b32_e32 v36, v36, v39, vcc
	v_rsq_f32_e32 v36, v36
	v_mul_f32_e32 v38, 0x45800000, v37
	v_cndmask_b32_e64 v37, v37, v38, s[0:1]
	v_mul_f32_e32 v39, 0x45800000, v36
	v_cndmask_b32_e32 v38, v36, v39, vcc
	v_mul_f32_e32 v36, 0.5, v37
	v_mul_f32_e32 v38, 0.5, v38
	v_pk_mul_f32 v[98:99], v[36:37], v[98:99] op_sel_hi:[0,1]
	v_pk_mul_f32 v[86:87], v[36:37], v[86:87] op_sel_hi:[0,1]
	v_pk_mul_f32 v[100:101], v[38:39], v[108:109] op_sel_hi:[0,1]
	v_pk_mul_f32 v[78:79], v[38:39], v[78:79] op_sel_hi:[0,1]
	v_pk_mul_f32 v[104:105], v[36:37], v[134:135] op_sel_hi:[0,1]
	v_pk_mul_f32 v[84:85], v[36:37], v[84:85] op_sel_hi:[0,1]
	v_pk_mul_f32 v[108:109], v[38:39], v[136:137] op_sel_hi:[0,1]
	v_pk_mul_f32 v[76:77], v[38:39], v[76:77] op_sel_hi:[0,1]
	v_pk_mul_f32 v[102:103], v[36:37], v[102:103] op_sel_hi:[0,1]
	v_pk_mul_f32 v[82:83], v[36:37], v[82:83] op_sel_hi:[0,1]
	v_pk_mul_f32 v[110:111], v[38:39], v[112:113] op_sel_hi:[0,1]
	v_pk_mul_f32 v[74:75], v[38:39], v[74:75] op_sel_hi:[0,1]
	v_pk_mul_f32 v[106:107], v[36:37], v[106:107] op_sel_hi:[0,1]
	v_pk_mul_f32 v[36:37], v[36:37], v[80:81] op_sel_hi:[0,1]
	v_pk_mul_f32 v[80:81], v[38:39], v[116:117] op_sel_hi:[0,1]
	v_pk_mul_f32 v[38:39], v[38:39], v[72:73] op_sel_hi:[0,1]
	v_pk_fma_f32 v[72:73], v[34:35], v[86:87], v[26:27]
	v_pk_fma_f32 v[86:87], v[32:33], v[98:99], v[24:25]
	v_pk_fma_f32 v[34:35], v[34:35], v[78:79], v[30:31]
	v_pk_fma_f32 v[32:33], v[32:33], v[100:101], v[28:29]
	v_cvt_pk_bf16_f32 v24, v86, v87
	v_cvt_pk_bf16_f32 v25, v72, v73
	v_cvt_pk_bf16_f32 v26, v32, v33
	v_cvt_pk_bf16_f32 v27, v34, v35
	global_store_dwordx2 v[66:67], v[24:25], off
	global_store_dwordx2 v[68:69], v[26:27], off
	s_nop 0
	v_pk_mul_f32 v[78:79], v[72:73], v[72:73]
	v_pk_mul_f32 v[98:99], v[86:87], v[86:87]
	v_pk_mul_f32 v[100:101], v[34:35], v[34:35]
	v_pk_mul_f32 v[26:27], v[154:155], v[158:159]
	v_pk_mul_f32 v[24:25], v[152:153], v[156:157]
	v_pk_fma_f32 v[28:29], v[26:27], v[84:85], v[18:19]
	v_pk_fma_f32 v[30:31], v[24:25], v[104:105], v[16:17]
	v_pk_fma_f32 v[26:27], v[26:27], v[76:77], v[22:23]
	v_pk_fma_f32 v[24:25], v[24:25], v[108:109], v[20:21]
	v_cvt_pk_bf16_f32 v16, v30, v31
	v_cvt_pk_bf16_f32 v17, v28, v29
	v_cvt_pk_bf16_f32 v18, v24, v25
	v_cvt_pk_bf16_f32 v19, v26, v27
	global_store_dwordx2 v[66:67], v[16:17], off offset:512
	global_store_dwordx2 v[68:69], v[18:19], off offset:512
	s_nop 0
	v_pk_mul_f32 v[76:77], v[32:33], v[32:33]
	v_pk_mov_b32 v[84:85], v[98:99], v[78:79] op_sel:[1,0]
	v_mov_b32_e32 v99, v79
	v_pk_mov_b32 v[78:79], v[76:77], v[100:101] op_sel:[1,0]
	v_mov_b32_e32 v77, v101
	v_pk_add_f32 v[84:85], v[84:85], v[98:99]
	v_pk_add_f32 v[76:77], v[78:79], v[76:77]
	v_pk_add_f32 v[78:79], v[84:85], v[84:85] op_sel:[0,1] op_sel_hi:[1,0]
	v_pk_mul_f32 v[84:85], v[30:31], v[30:31]
	v_pk_mul_f32 v[98:99], v[26:27], v[26:27]
	v_pk_add_f32 v[76:77], v[76:77], v[76:77] op_sel:[0,1] op_sel_hi:[1,0]
	v_pk_mul_f32 v[18:19], v[162:163], v[166:167]
	v_pk_mul_f32 v[16:17], v[160:161], v[164:165]
	v_pk_fma_f32 v[20:21], v[82:83], v[18:19], v[10:11]
	v_pk_fma_f32 v[22:23], v[102:103], v[16:17], v[8:9]
	v_pk_fma_f32 v[18:19], v[18:19], v[74:75], v[14:15]
	v_pk_fma_f32 v[16:17], v[16:17], v[110:111], v[12:13]
	v_cvt_pk_bf16_f32 v8, v22, v23
	v_cvt_pk_bf16_f32 v9, v20, v21
	v_cvt_pk_bf16_f32 v10, v16, v17
	v_cvt_pk_bf16_f32 v11, v18, v19
	global_store_dwordx2 v[66:67], v[8:9], off offset:1024
	global_store_dwordx2 v[68:69], v[10:11], off offset:1024
	s_nop 0
	v_pk_mul_f32 v[74:75], v[28:29], v[28:29]
	v_pk_mul_f32 v[82:83], v[24:25], v[24:25]
	v_pk_mov_b32 v[100:101], v[84:85], v[74:75] op_sel:[1,0]
	v_mov_b32_e32 v85, v75
	v_pk_mov_b32 v[74:75], v[82:83], v[98:99] op_sel:[1,0]
	v_mov_b32_e32 v83, v99
	v_pk_add_f32 v[84:85], v[100:101], v[84:85]
	v_pk_add_f32 v[74:75], v[74:75], v[82:83]
	v_pk_add_f32 v[82:83], v[84:85], v[84:85] op_sel:[0,1] op_sel_hi:[1,0]
	v_mul_f32_e32 v84, v23, v23
	v_mul_f32_e32 v98, v21, v21
	v_mul_f32_e32 v100, v17, v17
	v_mul_f32_e32 v102, v19, v19
	v_pk_add_f32 v[74:75], v[74:75], v[74:75] op_sel:[0,1] op_sel_hi:[1,0]
	v_pk_fma_f32 v[84:85], v[22:23], v[22:23], v[84:85] op_sel_hi:[1,1,0]
	v_pk_fma_f32 v[98:99], v[20:21], v[20:21], v[98:99] op_sel_hi:[1,1,0]
	v_pk_fma_f32 v[100:101], v[16:17], v[16:17], v[100:101] op_sel_hi:[1,1,0]
	v_pk_fma_f32 v[102:103], v[18:19], v[18:19], v[102:103] op_sel_hi:[1,1,0]
	v_pk_mul_f32 v[10:11], v[170:171], v[174:175]
	v_pk_mul_f32 v[8:9], v[168:169], v[172:173]
	v_pk_fma_f32 v[12:13], v[36:37], v[10:11], v[2:3]
	v_pk_fma_f32 v[14:15], v[106:107], v[8:9], v[0:1]
	v_pk_fma_f32 v[36:37], v[38:39], v[10:11], v[6:7]
	v_pk_fma_f32 v[38:39], v[80:81], v[8:9], v[4:5]
	v_cvt_pk_bf16_f32 v0, v14, v15
	v_cvt_pk_bf16_f32 v1, v12, v13
	v_cvt_pk_bf16_f32 v2, v38, v39
	v_cvt_pk_bf16_f32 v3, v36, v37
	global_store_dwordx2 v[66:67], v[0:1], off offset:1536
	global_store_dwordx2 v[68:69], v[2:3], off offset:1536
	s_nop 0
	v_mul_f32_e32 v79, v14, v14
	v_mul_f32_e32 v83, v15, v15
	v_mul_f32_e32 v85, v12, v12
	v_mul_f32_e32 v99, v13, v13
	v_mul_f32_e32 v101, v38, v38
	v_mul_f32_e32 v103, v39, v39
	v_mul_f32_e32 v77, v36, v36
	v_mul_f32_e32 v75, v37, v37
	v_pk_add_f32 v[66:67], v[78:79], v[82:83]
	v_pk_add_f32 v[68:69], v[84:85], v[98:99]
	v_pk_add_f32 v[78:79], v[100:101], v[102:103]
	v_pk_add_f32 v[74:75], v[76:77], v[74:75]
	v_pk_add_f32 v[66:67], v[66:67], v[68:69]
	v_pk_add_f32 v[68:69], v[78:79], v[74:75]
	v_mov_b32_e32 v75, v66
	v_mov_b32_e32 v74, v68
	v_mov_b32_e32 v66, v69
	v_pk_add_f32 v[66:67], v[74:75], v[66:67]
	ds_bpermute_b32 v69, v88, v67
	ds_bpermute_b32 v68, v88, v66
	s_waitcnt lgkmcnt(0)
	v_pk_add_f32 v[66:67], v[66:67], v[68:69]
	ds_bpermute_b32 v69, v89, v67
	ds_bpermute_b32 v68, v89, v66
	s_waitcnt lgkmcnt(0)
	v_pk_add_f32 v[66:67], v[66:67], v[68:69]
	ds_bpermute_b32 v69, v90, v67
	ds_bpermute_b32 v68, v90, v66
	s_waitcnt lgkmcnt(0)
	v_pk_add_f32 v[66:67], v[66:67], v[68:69]
	ds_bpermute_b32 v69, v91, v67
	ds_bpermute_b32 v68, v91, v66
	s_waitcnt lgkmcnt(0)
	v_pk_add_f32 v[66:67], v[66:67], v[68:69]
	ds_bpermute_b32 v69, v92, v67
	ds_bpermute_b32 v68, v92, v66
	s_waitcnt lgkmcnt(0)
	v_pk_add_f32 v[66:67], v[66:67], v[68:69]
	ds_bpermute_b32 v69, v93, v67
	ds_bpermute_b32 v68, v93, v66
	s_waitcnt lgkmcnt(0)
	v_pk_add_f32 v[66:67], v[66:67], v[68:69]
	s_nop 0
	v_pk_fma_f32 v[66:67], v[66:67], s[8:9], v[64:65] op_sel_hi:[1,0,0]
	s_add_i32 s9, s9, s20
	v_mul_f32_e32 v68, 0x4b800000, v67
	v_cmp_gt_f32_e64 s[0:1], s24, v67
	v_mul_f32_e32 v69, 0x4b800000, v66
	v_cmp_gt_f32_e32 vcc, s24, v66
	v_cndmask_b32_e64 v67, v67, v68, s[0:1]
	v_rsq_f32_e32 v67, v67
	v_cndmask_b32_e32 v66, v66, v69, vcc
	v_rsq_f32_e32 v68, v66
	s_cmp_lt_i32 s9, 0x8000
	v_mul_f32_e32 v66, 0x45800000, v67
	v_cndmask_b32_e64 v66, v67, v66, s[0:1]
	v_mul_f32_e32 v69, 0x45800000, v68
	v_cndmask_b32_e32 v68, v68, v69, vcc
	v_pk_mul_f32 v[74:75], v[86:87], v[66:67] op_sel_hi:[1,0]
	v_pk_mul_f32 v[72:73], v[72:73], v[66:67] op_sel_hi:[1,0]
	v_pk_add_f32 v[2:3], v[178:179], 1.0 op_sel_hi:[1,0]
	v_pk_add_f32 v[0:1], v[176:177], 1.0 op_sel_hi:[1,0]
	v_pk_mul_f32 v[2:3], v[182:183], v[2:3]
	v_pk_mul_f32 v[0:1], v[180:181], v[0:1]
	v_pk_mul_f32 v[32:33], v[32:33], v[68:69] op_sel_hi:[1,0]
	v_pk_mul_f32 v[34:35], v[34:35], v[68:69] op_sel_hi:[1,0]
	v_pk_fma_f32 v[4:5], v[2:3], v[72:73], v[186:187]
	v_pk_fma_f32 v[6:7], v[0:1], v[74:75], v[184:185]
	v_pk_fma_f32 v[2:3], v[2:3], v[34:35], v[186:187]
	v_pk_fma_f32 v[0:1], v[0:1], v[32:33], v[184:185]
	v_cvt_pk_bf16_f32 v6, v6, v7
	v_cvt_pk_bf16_f32 v7, v4, v5
	v_cvt_pk_bf16_f32 v0, v0, v1
	v_cvt_pk_bf16_f32 v1, v2, v3
	global_store_dwordx2 v[70:71], v[6:7], off
	global_store_dwordx2 v[70:71], v[0:1], off offset:2048
	s_nop 0
	v_pk_mul_f32 v[30:31], v[30:31], v[66:67] op_sel_hi:[1,0]
	v_pk_mul_f32 v[28:29], v[28:29], v[66:67] op_sel_hi:[1,0]
	v_pk_mul_f32 v[24:25], v[24:25], v[68:69] op_sel_hi:[1,0]
	v_pk_mul_f32 v[26:27], v[26:27], v[68:69] op_sel_hi:[1,0]
	v_pk_mul_f32 v[22:23], v[22:23], v[66:67] op_sel_hi:[1,0]
	v_pk_mul_f32 v[20:21], v[20:21], v[66:67] op_sel_hi:[1,0]
	v_pk_mul_f32 v[16:17], v[16:17], v[68:69] op_sel_hi:[1,0]
	v_pk_mul_f32 v[18:19], v[18:19], v[68:69] op_sel_hi:[1,0]
	v_pk_mul_f32 v[14:15], v[14:15], v[66:67] op_sel_hi:[1,0]
	v_pk_mul_f32 v[12:13], v[12:13], v[66:67] op_sel_hi:[1,0]
	v_pk_add_f32 v[2:3], v[190:191], 1.0 op_sel_hi:[1,0]
	v_pk_add_f32 v[0:1], v[188:189], 1.0 op_sel_hi:[1,0]
	v_pk_mul_f32 v[2:3], v[194:195], v[2:3]
	v_pk_mul_f32 v[0:1], v[192:193], v[0:1]
	v_pk_fma_f32 v[4:5], v[2:3], v[28:29], v[198:199]
	v_pk_fma_f32 v[6:7], v[0:1], v[30:31], v[196:197]
	v_pk_fma_f32 v[2:3], v[2:3], v[26:27], v[198:199]
	v_pk_fma_f32 v[0:1], v[0:1], v[24:25], v[196:197]
	v_cvt_pk_bf16_f32 v6, v6, v7
	v_cvt_pk_bf16_f32 v7, v4, v5
	v_cvt_pk_bf16_f32 v0, v0, v1
	v_cvt_pk_bf16_f32 v1, v2, v3
	global_store_dwordx2 v[70:71], v[6:7], off offset:512
	global_store_dwordx2 v[70:71], v[0:1], off offset:2560
	s_nop 0
	v_pk_add_f32 v[2:3], v[202:203], 1.0 op_sel_hi:[1,0]
	v_pk_add_f32 v[0:1], v[200:201], 1.0 op_sel_hi:[1,0]
	v_pk_mul_f32 v[2:3], v[206:207], v[2:3]
	v_pk_mul_f32 v[0:1], v[204:205], v[0:1]
	v_pk_fma_f32 v[4:5], v[20:21], v[2:3], v[222:223]
	v_pk_fma_f32 v[6:7], v[22:23], v[0:1], v[220:221]
	v_pk_fma_f32 v[2:3], v[18:19], v[2:3], v[222:223]
	v_pk_fma_f32 v[0:1], v[16:17], v[0:1], v[220:221]
	v_cvt_pk_bf16_f32 v6, v6, v7
	v_cvt_pk_bf16_f32 v7, v4, v5
	v_cvt_pk_bf16_f32 v0, v0, v1
	v_cvt_pk_bf16_f32 v1, v2, v3
	global_store_dwordx2 v[70:71], v[6:7], off offset:1024
	global_store_dwordx2 v[70:71], v[0:1], off offset:3072
	s_nop 0
	v_pk_mul_f32 v[16:17], v[38:39], v[68:69] op_sel_hi:[1,0]
	v_pk_mul_f32 v[18:19], v[36:37], v[68:69] op_sel_hi:[1,0]
	v_pk_add_f32 v[2:3], v[226:227], 1.0 op_sel_hi:[1,0]
	v_pk_add_f32 v[0:1], v[224:225], 1.0 op_sel_hi:[1,0]
	v_pk_mul_f32 v[2:3], v[230:231], v[2:3]
	v_pk_mul_f32 v[0:1], v[228:229], v[0:1]
	v_pk_fma_f32 v[4:5], v[12:13], v[2:3], v[234:235]
	v_pk_fma_f32 v[6:7], v[14:15], v[0:1], v[232:233]
	v_pk_fma_f32 v[2:3], v[18:19], v[2:3], v[234:235]
	v_pk_fma_f32 v[0:1], v[16:17], v[0:1], v[232:233]
	v_cvt_pk_bf16_f32 v6, v6, v7
	v_cvt_pk_bf16_f32 v7, v4, v5
	v_cvt_pk_bf16_f32 v0, v0, v1
	v_cvt_pk_bf16_f32 v1, v2, v3
	global_store_dwordx2 v[70:71], v[6:7], off offset:1536
	global_store_dwordx2 v[70:71], v[0:1], off offset:3584
	s_cbranch_scc1 .LBB0_316

.LBB0_1103:
	s_ashr_i32 s7, s6, 31
	s_add_i32 s0, s6, 1
	s_ashr_i32 s16, s9, 11
	s_add_i32 s2, s6, 2
	s_add_i32 s4, s6, 3
	s_lshl_b64 s[10:11], s[6:7], 11
	s_ashr_i32 s1, s0, 31
	s_mul_i32 s16, s16, 9
	s_ashr_i32 s3, s2, 31
	s_ashr_i32 s5, s4, 31
	v_lshl_add_u64 v[22:23], v[4:5], 0, s[10:11]
	v_lshl_add_u64 v[24:25], v[6:7], 0, s[10:11]
	s_lshl_b64 s[10:11], s[0:1], 11
	s_ashr_i32 s17, s16, 31
	global_load_dwordx4 v[0:3], v[10:11], off
	s_lshl_b64 s[18:19], s[2:3], 11
	s_lshl_b64 s[20:21], s[4:5], 11
	global_load_dwordx2 v[36:37], v[24:25], off
	global_load_dwordx2 v[38:39], v[22:23], off
	global_load_dwordx2 v[40:41], v[22:23], off offset:512
	global_load_dwordx2 v[42:43], v[22:23], off offset:1024
	global_load_dwordx2 v[44:45], v[22:23], off offset:1536
	global_load_dwordx2 v[46:47], v[22:23], off offset:2048
	global_load_dwordx2 v[50:51], v[22:23], off offset:2560
	global_load_dwordx2 v[76:77], v[24:25], off offset:512
	global_load_dwordx2 v[48:49], v[24:25], off offset:1024
	global_load_dwordx2 v[20:21], v[24:25], off offset:1536
	v_lshl_add_u64 v[26:27], v[6:7], 0, s[10:11]
	global_load_dwordx2 v[52:53], v[22:23], off offset:3072
	global_load_dwordx2 v[54:55], v[22:23], off offset:3584
	s_lshl_b64 s[10:11], s[16:17], 12
	s_add_u32 s10, s88, s10
	v_add_co_u32_e32 v30, vcc, s14, v22
	s_addc_u32 s11, s89, s11
	v_lshl_add_u64 v[28:29], v[6:7], 0, s[18:19]
	v_addc_co_u32_e32 v31, vcc, 0, v23, vcc
	v_lshl_add_u64 v[32:33], v[6:7], 0, s[20:21]
	global_load_dwordx2 v[60:61], v[26:27], off
	global_load_dwordx2 v[62:63], v[28:29], off
	global_load_dwordx2 v[66:67], v[32:33], off
	global_load_dwordx2 v[78:79], v[26:27], off offset:512
	global_load_dwordx2 v[56:57], v[26:27], off offset:1024
	global_load_dwordx2 v[22:23], v[26:27], off offset:1536
	global_load_dwordx2 v[84:85], v[30:31], off
	global_load_dwordx2 v[86:87], v[30:31], off offset:512
	global_load_dwordx2 v[88:89], v[30:31], off offset:1024
	global_load_dwordx2 v[90:91], v[30:31], off offset:1536
	global_load_dwordx2 v[80:81], v[28:29], off offset:512
	global_load_dwordx2 v[58:59], v[28:29], off offset:1024
	global_load_dwordx2 v[24:25], v[28:29], off offset:1536
	global_load_dwordx2 v[104:105], v[30:31], off offset:2048
	global_load_dwordx2 v[106:107], v[30:31], off offset:2560
	global_load_dwordx2 v[130:131], v[30:31], off offset:3072
	global_load_dwordx2 v[132:133], v[30:31], off offset:3584
	global_load_dwordx2 v[82:83], v[32:33], off offset:512
	global_load_dwordx2 v[64:65], v[32:33], off offset:1024
	global_load_dwordx2 v[26:27], v[32:33], off offset:1536
	s_add_u32 s10, s10, 0x8000
	s_addc_u32 s11, s11, 0
	global_load_dwordx4 v[126:129], v122, s[10:11]
	s_lshl_b64 s[0:1], s[0:1], 12
	s_lshl_b64 s[4:5], s[4:5], 12
	v_lshl_add_u64 v[30:31], v[8:9], 0, s[0:1]
	s_lshl_b64 s[2:3], s[2:3], 12
	v_lshl_add_u64 v[34:35], v[8:9], 0, s[4:5]
	v_lshl_add_u64 v[32:33], v[8:9], 0, s[2:3]
	s_lshl_b64 s[16:17], s[6:7], 12
	v_lshl_add_u64 v[28:29], v[8:9], 0, s[16:17]
	s_add_i32 s6, s6, s13
	global_load_dwordx4 v[220:223], v123, s[10:11]
	global_load_dwordx4 v[224:227], v[12:13], off
	global_load_dwordx4 v[228:231], v124, s[10:11]
	global_load_dwordx4 v[232:235], v[14:15], off
	global_load_dwordx4 v[236:239], v125, s[10:11]
	global_load_dwordx4 v[240:243], v[16:17], off
	s_waitcnt vmcnt(26)
	v_lshlrev_b32_e32 v138, 16, v60
	v_and_b32_e32 v113, 0xffff0000, v38
	v_and_b32_e32 v115, 0xffff0000, v39
	v_and_b32_e32 v97, 0xffff0000, v41
	v_and_b32_e32 v96, 0xffff0000, v40
	v_and_b32_e32 v69, 0xffff0000, v42
	v_and_b32_e32 v135, 0xffff0000, v46
	v_and_b32_e32 v137, 0xffff0000, v47
	v_lshlrev_b32_e32 v108, 16, v36
	v_and_b32_e32 v109, 0xffff0000, v36
	v_and_b32_e32 v71, 0xffff0000, v52
	v_and_b32_e32 v75, 0xffff0000, v53
	v_lshlrev_b32_e32 v110, 16, v37
	v_and_b32_e32 v111, 0xffff0000, v37
	v_lshlrev_b32_e32 v112, 16, v38
	v_lshlrev_b32_e32 v114, 16, v39
	v_lshlrev_b32_e32 v93, 16, v41
	v_lshlrev_b32_e32 v92, 16, v40
	v_lshlrev_b32_e32 v68, 16, v42
	v_lshlrev_b32_e32 v72, 16, v43
	v_and_b32_e32 v73, 0xffff0000, v43
	v_lshlrev_b32_e32 v41, 16, v44
	v_and_b32_e32 v37, 0xffff0000, v44
	v_lshlrev_b32_e32 v38, 16, v45
	v_and_b32_e32 v39, 0xffff0000, v45
	v_lshlrev_b32_e32 v134, 16, v46
	v_lshlrev_b32_e32 v136, 16, v47
	v_lshlrev_b32_e32 v95, 16, v51
	v_lshlrev_b32_e32 v94, 16, v50
	v_and_b32_e32 v99, 0xffff0000, v51
	v_and_b32_e32 v98, 0xffff0000, v50
	v_lshlrev_b32_e32 v70, 16, v52
	v_lshlrev_b32_e32 v74, 16, v53
	v_lshlrev_b32_e32 v47, 16, v54
	v_and_b32_e32 v43, 0xffff0000, v54
	v_lshlrev_b32_e32 v44, 16, v55
	v_and_b32_e32 v45, 0xffff0000, v55
	v_and_b32_e32 v139, 0xffff0000, v60
	v_lshlrev_b32_e32 v140, 16, v61
	v_and_b32_e32 v141, 0xffff0000, v61
	s_waitcnt vmcnt(24)
	v_lshlrev_b32_e32 v146, 16, v66
	v_and_b32_e32 v147, 0xffff0000, v66
	v_lshlrev_b32_e32 v148, 16, v67
	v_and_b32_e32 v149, 0xffff0000, v67
	v_mul_f32_e32 v36, v115, v115
	v_pk_mul_f32 v[150:151], v[96:97], v[96:97]
	v_mul_f32_e32 v40, v113, v113
	v_mul_f32_e32 v42, v69, v69
	v_mul_f32_e32 v50, v137, v137
	v_mul_f32_e32 v54, v135, v135
	v_mul_f32_e32 v60, v71, v71
	v_mul_f32_e32 v66, v75, v75
	s_waitcnt vmcnt(20)
	v_and_b32_e32 v159, 0xffff0000, v84
	v_and_b32_e32 v161, 0xffff0000, v85
	s_waitcnt vmcnt(19)
	v_and_b32_e32 v103, 0xffff0000, v87
	v_and_b32_e32 v102, 0xffff0000, v86
	s_waitcnt vmcnt(17)
	v_lshlrev_b32_e32 v55, 16, v90
	v_and_b32_e32 v51, 0xffff0000, v90
	s_waitcnt vmcnt(13)
	v_and_b32_e32 v163, 0xffff0000, v104
	v_and_b32_e32 v165, 0xffff0000, v105
	s_waitcnt vmcnt(10)
	v_lshlrev_b32_e32 v67, 16, v132
	v_and_b32_e32 v61, 0xffff0000, v132
	v_lshlrev_b32_e32 v142, 16, v62
	v_and_b32_e32 v143, 0xffff0000, v62
	v_lshlrev_b32_e32 v144, 16, v63
	v_and_b32_e32 v145, 0xffff0000, v63
	v_mul_f32_e32 v156, v38, v38
	v_mul_f32_e32 v46, v73, v73
	v_pk_mul_f32 v[154:155], v[98:99], v[98:99]
	v_lshlrev_b32_e32 v158, 16, v84
	v_lshlrev_b32_e32 v160, 16, v85
	v_lshlrev_b32_e32 v101, 16, v87
	v_lshlrev_b32_e32 v100, 16, v86
	v_lshlrev_b32_e32 v84, 16, v88
	v_and_b32_e32 v85, 0xffff0000, v88
	v_lshlrev_b32_e32 v88, 16, v89
	v_and_b32_e32 v89, 0xffff0000, v89
	v_lshlrev_b32_e32 v52, 16, v91
	v_and_b32_e32 v53, 0xffff0000, v91
	v_lshlrev_b32_e32 v162, 16, v104
	v_lshlrev_b32_e32 v164, 16, v105
	v_lshlrev_b32_e32 v105, 16, v107
	v_lshlrev_b32_e32 v104, 16, v106
	v_and_b32_e32 v107, 0xffff0000, v107
	v_and_b32_e32 v106, 0xffff0000, v106
	v_lshlrev_b32_e32 v86, 16, v130
	v_and_b32_e32 v87, 0xffff0000, v130
	v_lshlrev_b32_e32 v90, 16, v131
	v_and_b32_e32 v91, 0xffff0000, v131
	v_lshlrev_b32_e32 v62, 16, v133
	v_and_b32_e32 v63, 0xffff0000, v133
	v_pk_fma_f32 v[130:131], v[114:115], v[114:115], v[36:37] op_sel_hi:[1,1,0]
	v_pk_fma_f32 v[132:133], v[92:93], v[92:93], v[150:151]
	v_pk_fma_f32 v[150:151], v[112:113], v[112:113], v[40:41] op_sel_hi:[1,1,0]
	v_pk_fma_f32 v[166:167], v[68:69], v[68:69], v[42:43] op_sel_hi:[1,1,0]
	v_pk_fma_f32 v[170:171], v[136:137], v[136:137], v[50:51] op_sel_hi:[1,1,0]
	v_pk_fma_f32 v[172:173], v[134:135], v[134:135], v[54:55] op_sel_hi:[1,1,0]
	v_pk_fma_f32 v[174:175], v[70:71], v[70:71], v[60:61] op_sel_hi:[1,1,0]
	v_pk_fma_f32 v[176:177], v[74:75], v[74:75], v[66:67] op_sel_hi:[1,1,0]
	v_mul_f32_e32 v36, v161, v161
	v_pk_mul_f32 v[178:179], v[102:103], v[102:103]
	v_mul_f32_e32 v42, v159, v159
	v_mul_f32_e32 v60, v165, v165
	v_mul_f32_e32 v66, v163, v163
	v_mul_f32_e32 v186, v39, v39
	v_mov_b32_e32 v153, v41
	v_mul_f32_e32 v187, v44, v44
	v_mul_f32_e32 v188, v45, v45
	v_mov_b32_e32 v157, v47
	v_pk_fma_f32 v[168:169], v[72:73], v[72:73], v[46:47] op_sel_hi:[1,1,0]
	v_pk_fma_f32 v[154:155], v[94:95], v[94:95], v[154:155]
	v_mov_b32_e32 v181, v55
	v_mul_f32_e32 v54, v89, v89
	v_pk_mul_f32 v[182:183], v[106:107], v[106:107]
	v_mov_b32_e32 v185, v67
	v_mul_f32_e32 v180, v87, v87
	v_mul_f32_e32 v184, v91, v91
	v_mov_b32_e32 v40, v150
	v_mov_b32_e32 v152, v130
	v_pk_add_f32 v[130:131], v[150:151], v[130:131]
	v_mov_b32_e32 v167, v156
	v_mov_b32_e32 v46, v172
	v_mov_b32_e32 v156, v170
	v_pk_add_f32 v[150:151], v[172:173], v[170:171]
	v_pk_fma_f32 v[170:171], v[160:161], v[160:161], v[36:37] op_sel_hi:[1,1,0]
	v_pk_fma_f32 v[172:173], v[100:101], v[100:101], v[178:179]
	v_pk_fma_f32 v[178:179], v[158:159], v[158:159], v[42:43] op_sel_hi:[1,1,0]
	v_pk_fma_f32 v[190:191], v[164:165], v[164:165], v[60:61] op_sel_hi:[1,1,0]
	v_pk_fma_f32 v[192:193], v[162:163], v[162:163], v[66:67] op_sel_hi:[1,1,0]
	v_mul_f32_e32 v198, v37, v37
	v_mul_f32_e32 v199, v43, v43
	v_mul_f32_e32 v50, v85, v85
	v_pk_add_f32 v[132:133], v[132:133], v[132:133] op_sel:[0,1] op_sel_hi:[1,0]
	v_mov_b32_e32 v169, v186
	v_pk_add_f32 v[154:155], v[154:155], v[154:155] op_sel:[0,1] op_sel_hi:[1,0]
	v_mov_b32_e32 v175, v187
	v_mov_b32_e32 v177, v188
	v_pk_fma_f32 v[188:189], v[88:89], v[88:89], v[54:55] op_sel_hi:[1,1,0]
	v_pk_fma_f32 v[182:183], v[104:105], v[104:105], v[182:183]
	v_pk_fma_f32 v[194:195], v[86:87], v[86:87], v[180:181] op_sel_hi:[1,1,0]
	v_pk_fma_f32 v[196:197], v[90:91], v[90:91], v[184:185] op_sel_hi:[1,1,0]
	v_pk_mul_f32 v[152:153], v[40:41], v[152:153]
	v_pk_mul_f32 v[156:157], v[46:47], v[156:157]
	v_mov_b32_e32 v54, v178
	v_mov_b32_e32 v180, v170
	v_mov_b32_e32 v66, v192
	v_mov_b32_e32 v184, v190
	v_mul_f32_e32 v200, v51, v51
	v_mul_f32_e32 v201, v52, v52
	v_mul_f32_e32 v202, v53, v53
	v_mul_f32_e32 v203, v61, v61
	v_mul_f32_e32 v204, v62, v62
	v_mul_f32_e32 v205, v63, v63
	v_pk_fma_f32 v[186:187], v[84:85], v[84:85], v[50:51] op_sel_hi:[1,1,0]
	v_mov_b32_e32 v133, v198
	v_pk_add_f32 v[166:167], v[166:167], v[168:169]
	v_mov_b32_e32 v155, v199
	v_pk_add_f32 v[168:169], v[174:175], v[176:177]
	v_pk_add_f32 v[170:171], v[178:179], v[170:171]
	v_pk_add_f32 v[172:173], v[172:173], v[172:173] op_sel:[0,1] op_sel_hi:[1,0]
	v_pk_add_f32 v[174:175], v[192:193], v[190:191]
	v_pk_add_f32 v[176:177], v[182:183], v[182:183] op_sel:[0,1] op_sel_hi:[1,0]
	v_mov_b32_e32 v131, v153
	v_mov_b32_e32 v151, v157
	v_pk_mul_f32 v[152:153], v[54:55], v[180:181]
	v_pk_mul_f32 v[178:179], v[66:67], v[184:185]
	v_mov_b32_e32 v187, v201
	v_mov_b32_e32 v189, v202
	v_mov_b32_e32 v195, v204
	v_mov_b32_e32 v197, v205
	v_mov_b32_e32 v173, v200
	v_mov_b32_e32 v177, v203
	s_waitcnt vmcnt(0)
	v_pk_mul_f32 v[128:129], v[128:129], v[2:3]
	v_pk_mul_f32 v[126:127], v[126:127], v[0:1]
	v_pk_add_f32 v[0:1], v[130:131], v[132:133]
	v_pk_add_f32 v[2:3], v[150:151], v[154:155]
	v_mov_b32_e32 v171, v153
	v_mov_b32_e32 v175, v179
	v_pk_add_f32 v[156:157], v[186:187], v[188:189]
	v_pk_add_f32 v[180:181], v[194:195], v[196:197]
	v_pk_add_f32 v[0:1], v[0:1], v[166:167]
	v_pk_add_f32 v[2:3], v[2:3], v[168:169]
	v_pk_add_f32 v[130:131], v[170:171], v[172:173]
	v_pk_add_f32 v[132:133], v[174:175], v[176:177]
	v_mov_b32_e32 v150, v2
	v_mov_b32_e32 v151, v0
	v_mov_b32_e32 v0, v3
	v_pk_add_f32 v[2:3], v[130:131], v[156:157]
	v_pk_add_f32 v[130:131], v[132:133], v[180:181]
	v_pk_add_f32 v[0:1], v[150:151], v[0:1]
	v_mov_b32_e32 v132, v130
	v_mov_b32_e32 v133, v2
	v_mov_b32_e32 v2, v131
	ds_bpermute_b32 v131, v116, v1
	ds_bpermute_b32 v130, v116, v0
	v_pk_add_f32 v[2:3], v[132:133], v[2:3]
	ds_bpermute_b32 v133, v116, v3
	ds_bpermute_b32 v132, v116, v2
	v_mov_b32_e32 v50, v55
	s_waitcnt lgkmcnt(2)
	v_pk_add_f32 v[0:1], v[0:1], v[130:131]
	ds_bpermute_b32 v131, v117, v1
	ds_bpermute_b32 v130, v117, v0
	s_waitcnt lgkmcnt(2)
	v_pk_add_f32 v[2:3], v[2:3], v[132:133]
	ds_bpermute_b32 v133, v117, v3
	ds_bpermute_b32 v132, v117, v2
	v_mov_b32_e32 v60, v67
	s_waitcnt lgkmcnt(2)
	v_pk_add_f32 v[0:1], v[0:1], v[130:131]
	ds_bpermute_b32 v131, v118, v1
	ds_bpermute_b32 v130, v118, v0
	s_waitcnt lgkmcnt(2)
	v_pk_add_f32 v[2:3], v[2:3], v[132:133]
	ds_bpermute_b32 v133, v118, v3
	ds_bpermute_b32 v132, v118, v2
	s_waitcnt lgkmcnt(2)
	v_pk_add_f32 v[0:1], v[0:1], v[130:131]
	ds_bpermute_b32 v131, v119, v1
	ds_bpermute_b32 v130, v119, v0
	s_waitcnt lgkmcnt(2)
	v_pk_add_f32 v[2:3], v[2:3], v[132:133]
	ds_bpermute_b32 v133, v119, v3
	ds_bpermute_b32 v132, v119, v2
	s_waitcnt lgkmcnt(2)
	v_pk_add_f32 v[0:1], v[0:1], v[130:131]
	ds_bpermute_b32 v131, v120, v1
	ds_bpermute_b32 v130, v120, v0
	s_waitcnt lgkmcnt(2)
	v_pk_add_f32 v[2:3], v[2:3], v[132:133]
	ds_bpermute_b32 v133, v120, v3
	ds_bpermute_b32 v132, v120, v2
	s_waitcnt lgkmcnt(2)
	v_pk_add_f32 v[0:1], v[0:1], v[130:131]
	ds_bpermute_b32 v131, v121, v1
	ds_bpermute_b32 v130, v121, v0
	s_waitcnt lgkmcnt(2)
	v_pk_add_f32 v[2:3], v[2:3], v[132:133]
	ds_bpermute_b32 v133, v121, v3
	ds_bpermute_b32 v132, v121, v2
	s_waitcnt lgkmcnt(2)
	v_pk_add_f32 v[0:1], v[0:1], v[130:131]
	s_nop 0
	v_pk_fma_f32 v[0:1], v[0:1], s[8:9], v[18:19] op_sel_hi:[1,0,0]
	s_waitcnt lgkmcnt(0)
	v_pk_add_f32 v[2:3], v[2:3], v[132:133]
	v_mul_f32_e32 v36, 0x4b800000, v1
	v_mul_f32_e32 v40, 0x4b800000, v0
	v_cmp_gt_f32_e32 vcc, s15, v0
	v_pk_fma_f32 v[2:3], v[2:3], s[8:9], v[18:19] op_sel_hi:[1,0,0]
	v_cmp_gt_f32_e64 s[0:1], s15, v1
	v_cndmask_b32_e32 v0, v0, v40, vcc
	v_cmp_gt_f32_e64 s[4:5], s15, v3
	v_cndmask_b32_e64 v1, v1, v36, s[0:1]
	v_mul_f32_e32 v36, 0x4b800000, v3
	v_mul_f32_e32 v40, 0x4b800000, v2
	v_cmp_gt_f32_e64 s[2:3], s15, v2
	v_rsq_f32_e32 v1, v1
	v_rsq_f32_e32 v0, v0
	v_cndmask_b32_e64 v3, v3, v36, s[4:5]
	v_cndmask_b32_e64 v2, v2, v40, s[2:3]
	v_rsq_f32_e32 v3, v3
	v_rsq_f32_e32 v2, v2
	v_mul_f32_e32 v36, 0x45800000, v1
	v_mul_f32_e32 v40, 0x45800000, v0
	v_cndmask_b32_e64 v1, v1, v36, s[0:1]
	v_cndmask_b32_e32 v0, v0, v40, vcc
	v_mul_f32_e32 v36, 0x45800000, v3
	v_mul_f32_e32 v42, 0x45800000, v2
	v_mul_f32_e32 v40, 0.5, v1
	v_mul_f32_e32 v0, 0.5, v0
	v_cndmask_b32_e64 v1, v3, v36, s[4:5]
	v_cndmask_b32_e64 v2, v2, v42, s[2:3]
	v_mul_f32_e32 v46, 0.5, v1
	v_pk_mul_f32 v[112:113], v[40:41], v[112:113] op_sel_hi:[0,1]
	v_pk_mul_f32 v[114:115], v[40:41], v[114:115] op_sel_hi:[0,1]
	v_pk_mul_f32 v[130:131], v[0:1], v[134:135] op_sel_hi:[0,1]
	v_pk_mul_f32 v[132:133], v[0:1], v[136:137] op_sel_hi:[0,1]
	v_mul_f32_e32 v2, 0.5, v2
	v_pk_fma_f32 v[110:111], v[114:115], v[128:129], v[110:111]
	v_pk_fma_f32 v[108:109], v[112:113], v[126:127], v[108:109]
	v_pk_fma_f32 v[114:115], v[132:133], v[128:129], v[140:141]
	v_pk_fma_f32 v[112:113], v[130:131], v[126:127], v[138:139]
	v_pk_mul_f32 v[130:131], v[46:47], v[158:159] op_sel_hi:[0,1]
	v_pk_mul_f32 v[132:133], v[46:47], v[160:161] op_sel_hi:[0,1]
	v_pk_mul_f32 v[134:135], v[2:3], v[162:163] op_sel_hi:[0,1]
	v_pk_mul_f32 v[136:137], v[2:3], v[164:165] op_sel_hi:[0,1]
	global_store_dwordx4 v[28:29], v[108:111], off
	global_store_dwordx4 v[30:31], v[112:115], off
	v_lshlrev_b32_e32 v138, 16, v82
	v_pk_fma_f32 v[110:111], v[128:129], v[132:133], v[144:145]
	v_pk_fma_f32 v[108:109], v[126:127], v[130:131], v[142:143]
	v_pk_fma_f32 v[114:115], v[128:129], v[136:137], v[148:149]
	v_pk_fma_f32 v[112:113], v[126:127], v[134:135], v[146:147]
	global_store_dwordx4 v[32:33], v[108:111], off
	global_store_dwordx4 v[34:35], v[112:115], off
	s_nop 0
	v_lshlrev_b32_e32 v126, 16, v76
	v_and_b32_e32 v127, 0xffff0000, v76
	v_lshlrev_b32_e32 v128, 16, v77
	v_and_b32_e32 v129, 0xffff0000, v77
	v_mov_b32_e32 v76, v93
	v_mov_b32_e32 v77, v97
	v_mov_b32_e32 v93, v96
	v_lshlrev_b32_e32 v130, 16, v78
	v_and_b32_e32 v131, 0xffff0000, v78
	v_lshlrev_b32_e32 v132, 16, v79
	v_and_b32_e32 v133, 0xffff0000, v79
	v_lshlrev_b32_e32 v134, 16, v80
	v_and_b32_e32 v135, 0xffff0000, v80
	v_lshlrev_b32_e32 v136, 16, v81
	v_and_b32_e32 v137, 0xffff0000, v81
	v_and_b32_e32 v139, 0xffff0000, v82
	v_lshlrev_b32_e32 v140, 16, v83
	v_and_b32_e32 v141, 0xffff0000, v83
	v_mov_b32_e32 v78, v95
	v_mov_b32_e32 v79, v99
	v_mov_b32_e32 v95, v98
	v_mov_b32_e32 v80, v101
	v_mov_b32_e32 v81, v103
	v_mov_b32_e32 v82, v105
	v_mov_b32_e32 v83, v107
	v_mov_b32_e32 v101, v102
	v_mov_b32_e32 v105, v106
	v_pk_mul_f32 v[96:97], v[40:41], v[76:77] op_sel_hi:[0,1]
	v_pk_mul_f32 v[76:77], v[40:41], v[92:93] op_sel_hi:[0,1]
	v_pk_mul_f32 v[92:93], v[0:1], v[78:79] op_sel_hi:[0,1]
	v_pk_mul_f32 v[94:95], v[0:1], v[94:95] op_sel_hi:[0,1]
	v_pk_mul_f32 v[98:99], v[46:47], v[80:81] op_sel_hi:[0,1]
	v_pk_mul_f32 v[100:101], v[46:47], v[100:101] op_sel_hi:[0,1]
	v_pk_mul_f32 v[102:103], v[2:3], v[82:83] op_sel_hi:[0,1]
	v_pk_mul_f32 v[104:105], v[2:3], v[104:105] op_sel_hi:[0,1]
	v_pk_mul_f32 v[84:85], v[46:47], v[84:85] op_sel_hi:[0,1]
	v_pk_mul_f32 v[86:87], v[2:3], v[86:87] op_sel_hi:[0,1]
	v_mov_b32_e32 v36, v41
	v_mov_b32_e32 v42, v47
	s_add_i32 s9, s9, s12
	s_cmpk_lt_i32 s9, 0x4000
	v_pk_mul_f32 v[106:107], v[222:223], v[226:227]
	v_pk_mul_f32 v[108:109], v[220:221], v[224:225]
	v_pk_fma_f32 v[78:79], v[96:97], v[106:107], v[128:129]
	v_pk_fma_f32 v[76:77], v[76:77], v[108:109], v[126:127]
	v_pk_fma_f32 v[80:81], v[94:95], v[108:109], v[130:131]
	v_pk_fma_f32 v[82:83], v[92:93], v[106:107], v[132:133]
	v_pk_fma_f32 v[92:93], v[100:101], v[108:109], v[134:135]
	v_pk_fma_f32 v[94:95], v[98:99], v[106:107], v[136:137]
	v_pk_fma_f32 v[96:97], v[108:109], v[104:105], v[138:139]
	v_pk_fma_f32 v[98:99], v[106:107], v[102:103], v[140:141]
	global_store_dwordx4 v[28:29], v[76:79], off offset:1024
	global_store_dwordx4 v[30:31], v[80:83], off offset:1024
	global_store_dwordx4 v[32:33], v[92:95], off offset:1024
	global_store_dwordx4 v[34:35], v[96:99], off offset:1024
	s_nop 0
	v_lshlrev_b32_e32 v92, 16, v48
	v_and_b32_e32 v93, 0xffff0000, v48
	v_lshlrev_b32_e32 v48, 16, v49
	v_and_b32_e32 v49, 0xffff0000, v49
	v_lshlrev_b32_e32 v94, 16, v56
	v_and_b32_e32 v95, 0xffff0000, v56
	v_lshlrev_b32_e32 v96, 16, v57
	v_and_b32_e32 v97, 0xffff0000, v57
	v_lshlrev_b32_e32 v98, 16, v58
	v_and_b32_e32 v99, 0xffff0000, v58
	v_lshlrev_b32_e32 v100, 16, v59
	v_and_b32_e32 v101, 0xffff0000, v59
	v_pk_mul_f32 v[58:59], v[40:41], v[72:73] op_sel_hi:[0,1]
	v_pk_mul_f32 v[56:57], v[40:41], v[68:69] op_sel_hi:[0,1]
	v_lshlrev_b32_e32 v102, 16, v64
	v_and_b32_e32 v103, 0xffff0000, v64
	v_lshlrev_b32_e32 v64, 16, v65
	v_and_b32_e32 v65, 0xffff0000, v65
	v_pk_mul_f32 v[72:73], v[0:1], v[74:75] op_sel_hi:[0,1]
	v_pk_mul_f32 v[68:69], v[0:1], v[70:71] op_sel_hi:[0,1]
	v_pk_mul_f32 v[74:75], v[46:47], v[88:89] op_sel_hi:[0,1]
	v_pk_mul_f32 v[88:89], v[2:3], v[90:91] op_sel_hi:[0,1]
	v_pk_mul_f32 v[78:79], v[230:231], v[234:235]
	v_pk_mul_f32 v[76:77], v[228:229], v[232:233]
	v_pk_fma_f32 v[58:59], v[58:59], v[78:79], v[48:49]
	v_pk_fma_f32 v[56:57], v[56:57], v[76:77], v[92:93]
	v_pk_fma_f32 v[68:69], v[68:69], v[76:77], v[94:95]
	v_pk_fma_f32 v[70:71], v[72:73], v[78:79], v[96:97]
	v_pk_fma_f32 v[72:73], v[84:85], v[76:77], v[98:99]
	v_pk_fma_f32 v[74:75], v[74:75], v[78:79], v[100:101]
	v_pk_fma_f32 v[76:77], v[86:87], v[76:77], v[102:103]
	v_pk_fma_f32 v[78:79], v[88:89], v[78:79], v[64:65]
	global_store_dwordx4 v[28:29], v[56:59], off offset:2048
	global_store_dwordx4 v[30:31], v[68:71], off offset:2048
	global_store_dwordx4 v[32:33], v[72:75], off offset:2048
	global_store_dwordx4 v[34:35], v[76:79], off offset:2048
	s_nop 0
	v_lshlrev_b32_e32 v48, 16, v20
	v_and_b32_e32 v49, 0xffff0000, v20
	v_lshlrev_b32_e32 v20, 16, v21
	v_and_b32_e32 v21, 0xffff0000, v21
	v_lshlrev_b32_e32 v72, 16, v24
	v_and_b32_e32 v73, 0xffff0000, v24
	v_lshlrev_b32_e32 v74, 16, v25
	v_and_b32_e32 v75, 0xffff0000, v25
	v_lshlrev_b32_e32 v76, 16, v26
	v_and_b32_e32 v77, 0xffff0000, v26
	v_lshlrev_b32_e32 v78, 16, v27
	v_and_b32_e32 v79, 0xffff0000, v27
	v_pk_mul_f32 v[24:25], v[40:41], v[38:39] op_sel_hi:[0,1]
	v_pk_mul_f32 v[26:27], v[40:41], v[36:37] op_sel_hi:[0,1]
	v_pk_mul_f32 v[38:39], v[0:1], v[42:43] op_sel_hi:[0,1]
	v_pk_mul_f32 v[40:41], v[46:47], v[52:53] op_sel_hi:[0,1]
	v_pk_mul_f32 v[42:43], v[46:47], v[50:51] op_sel_hi:[0,1]
	v_lshlrev_b32_e32 v64, 16, v22
	v_and_b32_e32 v65, 0xffff0000, v22
	v_lshlrev_b32_e32 v22, 16, v23
	v_and_b32_e32 v23, 0xffff0000, v23
	v_pk_mul_f32 v[36:37], v[0:1], v[44:45] op_sel_hi:[0,1]
	v_pk_mul_f32 v[44:45], v[2:3], v[62:63] op_sel_hi:[0,1]
	v_pk_mul_f32 v[46:47], v[2:3], v[60:61] op_sel_hi:[0,1]
	v_pk_mul_f32 v[50:51], v[238:239], v[242:243]
	v_pk_mul_f32 v[52:53], v[236:237], v[240:241]
	v_pk_fma_f32 v[2:3], v[24:25], v[50:51], v[20:21]
	v_pk_fma_f32 v[0:1], v[26:27], v[52:53], v[48:49]
	v_pk_fma_f32 v[20:21], v[38:39], v[52:53], v[64:65]
	v_pk_fma_f32 v[22:23], v[36:37], v[50:51], v[22:23]
	v_pk_fma_f32 v[24:25], v[42:43], v[52:53], v[72:73]
	v_pk_fma_f32 v[26:27], v[40:41], v[50:51], v[74:75]
	v_pk_fma_f32 v[36:37], v[46:47], v[52:53], v[76:77]
	v_pk_fma_f32 v[38:39], v[44:45], v[50:51], v[78:79]
	global_store_dwordx4 v[28:29], v[0:3], off offset:3072
	global_store_dwordx4 v[30:31], v[20:23], off offset:3072
	global_store_dwordx4 v[32:33], v[24:27], off offset:3072
	global_store_dwordx4 v[34:35], v[36:39], off offset:3072
	s_cbranch_scc1 .LBB0_1103
